# v30 + skip of the grid barrier after the very last FFN-out (kernel ends there)
# baseline (speedup 1.0000x reference)
.LBB0_1608:
	v_readlane_b32 s4, v254, 33
	s_cmp_lg_u32 s4, 6
	s_cbranch_scc1 .Lko_fin_no
	s_cmp_eq_u64 s[14:15], 0
	s_cbranch_scc1 .Lko_fin_no
	s_waitcnt vmcnt(0) lgkmcnt(0)
	s_endpgm
